# combined + strategy 4: per-segment s_setprio toggles removed in GEMM loops, one static s_setprio 1 for the second wave half (wr==1) per unit
# speedup vs baseline: 1.0046x; 1.0046x over previous
.LBB0_119:
	s_ashr_i32 s21, s20, 31
	s_lshl_b64 s[26:27], s[20:21], 20
	s_add_u32 s26, s14, s26
	s_addc_u32 s27, s15, s27
	s_and_b64 s[28:29], s[28:29], exec
	s_cselect_b32 s21, s27, s43
	s_cselect_b32 s50, s26, s42
	s_add_u32 s40, s40, 0x80080
	s_addc_u32 s41, s41, 0
	s_add_u32 s51, s42, 0x100
	v_mov_b32_e32 v0, 0
	s_addc_u32 s52, s43, 0
	s_mov_b32 s53, -2
	s_waitcnt lgkmcnt(0)
	v_mov_b32_e32 v1, v0
	v_mov_b32_e32 v2, v0
	v_mov_b32_e32 v3, v0
	v_mov_b32_e32 v4, v0
	v_mov_b32_e32 v5, v0
	v_mov_b32_e32 v6, v0
	v_mov_b32_e32 v7, v0
	v_mov_b32_e32 v16, v0
	v_mov_b32_e32 v17, v0
	v_mov_b32_e32 v18, v0
	v_mov_b32_e32 v19, v0
	v_mov_b32_e32 v20, v0
	v_mov_b32_e32 v21, v0
	v_mov_b32_e32 v22, v0
	v_mov_b32_e32 v23, v0
	s_waitcnt vmcnt(0)
	v_mov_b32_e32 v34, v0
	v_mov_b32_e32 v35, v0
	v_mov_b32_e32 v36, v0
	v_mov_b32_e32 v37, v0
	v_mov_b32_e32 v38, v0
	v_mov_b32_e32 v39, v0
	v_mov_b32_e32 v40, v0
	v_mov_b32_e32 v41, v0
	v_mov_b32_e32 v50, v0
	v_mov_b32_e32 v51, v0
	v_mov_b32_e32 v52, v0
	v_mov_b32_e32 v53, v0
	v_mov_b32_e32 v54, v0
	v_mov_b32_e32 v55, v0
	v_mov_b32_e32 v56, v0
	v_mov_b32_e32 v57, v0
	v_mov_b32_e32 v8, v0
	v_mov_b32_e32 v9, v0
	v_mov_b32_e32 v10, v0
	v_mov_b32_e32 v11, v0
	v_mov_b32_e32 v12, v0
	v_mov_b32_e32 v13, v0
	v_mov_b32_e32 v14, v0
	v_mov_b32_e32 v15, v0
	v_mov_b32_e32 v24, v0
	v_mov_b32_e32 v25, v0
	v_mov_b32_e32 v26, v0
	v_mov_b32_e32 v27, v0
	v_mov_b32_e32 v28, v0
	v_mov_b32_e32 v29, v0
	v_mov_b32_e32 v30, v0
	v_mov_b32_e32 v31, v0
	v_mov_b32_e32 v42, v0
	v_mov_b32_e32 v43, v0
	v_mov_b32_e32 v44, v0
	v_mov_b32_e32 v45, v0
	v_mov_b32_e32 v46, v0
	v_mov_b32_e32 v47, v0
	v_mov_b32_e32 v48, v0
	v_mov_b32_e32 v49, v0
	v_mov_b32_e32 v58, v0
	v_mov_b32_e32 v59, v0
	v_mov_b32_e32 v60, v0
	v_mov_b32_e32 v61, v0
	v_mov_b32_e32 v62, v0
	v_mov_b32_e32 v63, v0
	v_mov_b32_e32 v64, v0
	v_mov_b32_e32 v65, v0
	v_mov_b32_e32 v66, v0
	v_mov_b32_e32 v67, v0
	v_mov_b32_e32 v68, v0
	v_mov_b32_e32 v69, v0
	v_mov_b32_e32 v70, v0
	v_mov_b32_e32 v71, v0
	v_mov_b32_e32 v72, v0
	v_mov_b32_e32 v73, v0
	v_mov_b32_e32 v82, v0
	v_mov_b32_e32 v83, v0
	v_mov_b32_e32 v84, v0
	v_mov_b32_e32 v85, v0
	v_mov_b32_e32 v86, v0
	v_mov_b32_e32 v87, v0
	v_mov_b32_e32 v88, v0
	v_mov_b32_e32 v89, v0
	v_mov_b32_e32 v98, v0
	v_mov_b32_e32 v99, v0
	v_mov_b32_e32 v100, v0
	v_mov_b32_e32 v101, v0
	v_mov_b32_e32 v102, v0
	v_mov_b32_e32 v103, v0
	v_mov_b32_e32 v104, v0
	v_mov_b32_e32 v105, v0
	v_mov_b32_e32 v114, v0
	v_mov_b32_e32 v115, v0
	v_mov_b32_e32 v116, v0
	v_mov_b32_e32 v117, v0
	v_mov_b32_e32 v118, v0
	v_mov_b32_e32 v119, v0
	v_mov_b32_e32 v120, v0
	v_mov_b32_e32 v121, v0
	v_mov_b32_e32 v74, v0
	v_mov_b32_e32 v75, v0
	v_mov_b32_e32 v76, v0
	v_mov_b32_e32 v77, v0
	v_mov_b32_e32 v78, v0
	v_mov_b32_e32 v79, v0
	v_mov_b32_e32 v80, v0
	v_mov_b32_e32 v81, v0
	v_mov_b32_e32 v90, v0
	v_mov_b32_e32 v91, v0
	v_mov_b32_e32 v92, v0
	v_mov_b32_e32 v93, v0
	v_mov_b32_e32 v94, v0
	v_mov_b32_e32 v95, v0
	v_mov_b32_e32 v96, v0
	v_mov_b32_e32 v97, v0
	v_mov_b32_e32 v106, v0
	v_mov_b32_e32 v107, v0
	v_mov_b32_e32 v108, v0
	v_mov_b32_e32 v109, v0
	v_mov_b32_e32 v110, v0
	v_mov_b32_e32 v111, v0
	v_mov_b32_e32 v112, v0
	v_mov_b32_e32 v113, v0
	v_mov_b32_e32 v122, v0
	v_mov_b32_e32 v123, v0
	v_mov_b32_e32 v124, v0
	v_mov_b32_e32 v125, v0
	v_mov_b32_e32 v126, v0
	v_mov_b32_e32 v127, v0
	v_mov_b32_e32 v128, v0
	v_mov_b32_e32 v129, v0
	s_and_b64 vcc, exec, s[18:19]
	s_cbranch_vccnz .Lprio_skip_120
	s_setprio 1
.Lprio_skip_120:
.LBB0_120:
	s_add_u32 s28, s40, 0xfff80080
	s_addc_u32 s29, s41, -1
	s_add_i32 s54, 0, 0x10000
	s_cmp_eq_u32 s53, 28
	s_cselect_b32 s29, s23, s29
	s_cselect_b32 s28, s22, s28
	s_cselect_b32 s43, s21, s52
	s_cselect_b32 s42, s50, s51
	s_add_i32 s56, 0, 0x14000
	v_add_u32_e32 v142, s54, v212
	v_add_u32_e32 v158, s56, v212
	ds_read_b128 v[130:133], v142
	ds_read_b128 v[134:137], v142 offset:1024
	ds_read_b128 v[138:141], v142 offset:2048
	ds_read_b128 v[142:145], v142 offset:3072
	ds_read_b128 v[146:149], v158
	ds_read_b128 v[150:153], v158 offset:1024
	ds_read_b128 v[154:157], v158 offset:2048
	ds_read_b128 v[158:161], v158 offset:3072
	s_add_i32 m0, s24, 0xc000
	ds_read_b128 v[162:165], v213
	ds_read_b128 v[166:169], v213 offset:1024
	ds_read_b128 v[170:173], v213 offset:2048
	ds_read_b128 v[174:177], v213 offset:3072
	ds_read_b128 v[188:191], v213 offset:4096
	ds_read_b128 v[192:195], v213 offset:5120
	ds_read_b128 v[196:199], v213 offset:6144
	ds_read_b128 v[200:203], v213 offset:7168
	global_load_lds_dwordx4 v184, s[40:41]
	s_add_i32 m0, s24, 0xe000
	s_nop 0
	global_load_lds_dwordx4 v186, s[40:41]
	s_waitcnt vmcnt(8)
	s_waitcnt lgkmcnt(0)
	s_barrier
	v_mfma_f32_16x16x32_bf16 v[126:129], v[130:133], v[162:165], v[126:129]
	v_mfma_f32_16x16x32_bf16 v[126:129], v[134:137], v[166:169], v[126:129]
	v_mfma_f32_16x16x32_bf16 v[122:125], v[142:145], v[166:169], v[122:125]
	v_mfma_f32_16x16x32_bf16 v[122:125], v[138:141], v[162:165], v[122:125]
	v_mfma_f32_16x16x32_bf16 v[106:109], v[138:141], v[170:173], v[106:109]
	v_mfma_f32_16x16x32_bf16 v[106:109], v[142:145], v[174:177], v[106:109]
	v_mfma_f32_16x16x32_bf16 v[110:113], v[134:137], v[174:177], v[110:113]
	v_mfma_f32_16x16x32_bf16 v[110:113], v[130:133], v[170:173], v[110:113]
	v_mfma_f32_16x16x32_bf16 v[94:97], v[130:133], v[188:191], v[94:97]
	v_mfma_f32_16x16x32_bf16 v[94:97], v[134:137], v[192:195], v[94:97]
	v_mfma_f32_16x16x32_bf16 v[90:93], v[142:145], v[192:195], v[90:93]
	v_mfma_f32_16x16x32_bf16 v[90:93], v[138:141], v[188:191], v[90:93]
	v_mfma_f32_16x16x32_bf16 v[74:77], v[138:141], v[196:199], v[74:77]
	v_mfma_f32_16x16x32_bf16 v[74:77], v[142:145], v[200:203], v[74:77]
	v_mfma_f32_16x16x32_bf16 v[78:81], v[134:137], v[200:203], v[78:81]
	v_mfma_f32_16x16x32_bf16 v[78:81], v[130:133], v[196:199], v[78:81]
	v_mfma_f32_16x16x32_bf16 v[118:121], v[146:149], v[162:165], v[118:121]
	v_mfma_f32_16x16x32_bf16 v[118:121], v[150:153], v[166:169], v[118:121]
	v_mfma_f32_16x16x32_bf16 v[114:117], v[158:161], v[166:169], v[114:117]
	v_mfma_f32_16x16x32_bf16 v[114:117], v[154:157], v[162:165], v[114:117]
	v_mfma_f32_16x16x32_bf16 v[98:101], v[154:157], v[170:173], v[98:101]
	v_mfma_f32_16x16x32_bf16 v[98:101], v[158:161], v[174:177], v[98:101]
	v_mfma_f32_16x16x32_bf16 v[102:105], v[150:153], v[174:177], v[102:105]
	v_mfma_f32_16x16x32_bf16 v[102:105], v[146:149], v[170:173], v[102:105]
	v_mfma_f32_16x16x32_bf16 v[86:89], v[146:149], v[188:191], v[86:89]
	v_mfma_f32_16x16x32_bf16 v[86:89], v[150:153], v[192:195], v[86:89]
	v_mfma_f32_16x16x32_bf16 v[82:85], v[158:161], v[192:195], v[82:85]
	v_mfma_f32_16x16x32_bf16 v[82:85], v[154:157], v[188:191], v[82:85]
	v_mfma_f32_16x16x32_bf16 v[66:69], v[154:157], v[196:199], v[66:69]
	v_mfma_f32_16x16x32_bf16 v[66:69], v[158:161], v[200:203], v[66:69]
	v_mfma_f32_16x16x32_bf16 v[70:73], v[150:153], v[200:203], v[70:73]
	v_mfma_f32_16x16x32_bf16 v[70:73], v[146:149], v[196:199], v[70:73]
	s_barrier
	s_add_i32 s54, s54, s1
	v_lshl_add_u64 v[204:205], s[42:43], 0, v[32:33]
	s_mov_b32 m0, s54
	ds_read_b128 v[162:165], v213 offset:16384
	ds_read_b128 v[166:169], v213 offset:17408
	ds_read_b128 v[170:173], v213 offset:18432
	ds_read_b128 v[174:177], v213 offset:19456
	ds_read_b128 v[188:191], v213 offset:20480
	ds_read_b128 v[192:195], v213 offset:21504
	ds_read_b128 v[196:199], v213 offset:22528
	ds_read_b128 v[200:203], v213 offset:23552
	global_load_lds_dwordx4 v[204:205], off
	s_add_i32 m0, s54, 0x2000
	s_add_u32 s54, s42, 0x80000
	v_lshl_add_u64 v[206:207], s[42:43], 0, v[182:183]
	s_addc_u32 s55, s43, 0
	s_add_i32 s56, s56, s1
	global_load_lds_dwordx4 v[206:207], off
	s_mov_b32 m0, s56
	v_lshl_add_u64 v[214:215], s[28:29], 0, v[180:181]
	global_load_lds_dwordx4 v32, s[54:55]
	s_add_i32 m0, s56, 0x2000
	s_nop 0
	global_load_lds_dwordx4 v182, s[54:55]
	v_lshl_add_u64 v[208:209], s[28:29], 0, v[178:179]
	s_mov_b32 m0, s24
	s_nop 0
	global_load_lds_dwordx4 v[208:209], off
	s_mov_b32 m0, s25
	s_nop 0
	global_load_lds_dwordx4 v[214:215], off
	s_waitcnt vmcnt(8)
	s_waitcnt lgkmcnt(0)
	s_barrier
	v_mfma_f32_16x16x32_bf16 v[62:65], v[130:133], v[162:165], v[62:65]
	v_mfma_f32_16x16x32_bf16 v[62:65], v[134:137], v[166:169], v[62:65]
	v_mfma_f32_16x16x32_bf16 v[58:61], v[142:145], v[166:169], v[58:61]
	v_mfma_f32_16x16x32_bf16 v[58:61], v[138:141], v[162:165], v[58:61]
	v_mfma_f32_16x16x32_bf16 v[42:45], v[138:141], v[170:173], v[42:45]
	v_mfma_f32_16x16x32_bf16 v[42:45], v[142:145], v[174:177], v[42:45]
	v_mfma_f32_16x16x32_bf16 v[46:49], v[134:137], v[174:177], v[46:49]
	v_mfma_f32_16x16x32_bf16 v[46:49], v[130:133], v[170:173], v[46:49]
	v_mfma_f32_16x16x32_bf16 v[28:31], v[130:133], v[188:191], v[28:31]
	v_mfma_f32_16x16x32_bf16 v[28:31], v[134:137], v[192:195], v[28:31]
	v_mfma_f32_16x16x32_bf16 v[24:27], v[142:145], v[192:195], v[24:27]
	v_mfma_f32_16x16x32_bf16 v[24:27], v[138:141], v[188:191], v[24:27]
	v_mfma_f32_16x16x32_bf16 v[8:11], v[138:141], v[196:199], v[8:11]
	v_mfma_f32_16x16x32_bf16 v[8:11], v[142:145], v[200:203], v[8:11]
	v_mfma_f32_16x16x32_bf16 v[12:15], v[134:137], v[200:203], v[12:15]
	v_mfma_f32_16x16x32_bf16 v[12:15], v[130:133], v[196:199], v[12:15]
	v_mfma_f32_16x16x32_bf16 v[54:57], v[146:149], v[162:165], v[54:57]
	v_mfma_f32_16x16x32_bf16 v[54:57], v[150:153], v[166:169], v[54:57]
	v_mfma_f32_16x16x32_bf16 v[50:53], v[158:161], v[166:169], v[50:53]
	v_mfma_f32_16x16x32_bf16 v[50:53], v[154:157], v[162:165], v[50:53]
	v_mfma_f32_16x16x32_bf16 v[34:37], v[154:157], v[170:173], v[34:37]
	v_mfma_f32_16x16x32_bf16 v[34:37], v[158:161], v[174:177], v[34:37]
	v_mfma_f32_16x16x32_bf16 v[38:41], v[150:153], v[174:177], v[38:41]
	v_mfma_f32_16x16x32_bf16 v[38:41], v[146:149], v[170:173], v[38:41]
	v_mfma_f32_16x16x32_bf16 v[20:23], v[146:149], v[188:191], v[20:23]
	v_mfma_f32_16x16x32_bf16 v[20:23], v[150:153], v[192:195], v[20:23]
	v_mfma_f32_16x16x32_bf16 v[16:19], v[158:161], v[192:195], v[16:19]
	v_mfma_f32_16x16x32_bf16 v[16:19], v[154:157], v[188:191], v[16:19]
	v_mfma_f32_16x16x32_bf16 v[0:3], v[154:157], v[196:199], v[0:3]
	v_mfma_f32_16x16x32_bf16 v[0:3], v[158:161], v[200:203], v[0:3]
	v_mfma_f32_16x16x32_bf16 v[4:7], v[150:153], v[200:203], v[4:7]
	v_mfma_f32_16x16x32_bf16 v[4:7], v[146:149], v[196:199], v[4:7]
	s_barrier
	s_add_i32 s54, 0, 0x18000
	s_add_i32 s55, 0, 0x1c000
	v_add_u32_e32 v142, s54, v212
	v_add_u32_e32 v158, s55, v212
	ds_read_b128 v[130:133], v142
	ds_read_b128 v[134:137], v142 offset:1024
	ds_read_b128 v[138:141], v142 offset:2048
	ds_read_b128 v[142:145], v142 offset:3072
	ds_read_b128 v[146:149], v158
	ds_read_b128 v[150:153], v158 offset:1024
	ds_read_b128 v[154:157], v158 offset:2048
	ds_read_b128 v[158:161], v158 offset:3072
	s_add_u32 s28, s28, 0x80000
	s_addc_u32 s29, s29, 0
	s_mov_b32 m0, s33
	ds_read_b128 v[162:165], v213 offset:32768
	ds_read_b128 v[166:169], v213 offset:33792
	ds_read_b128 v[170:173], v213 offset:34816
	ds_read_b128 v[174:177], v213 offset:35840
	ds_read_b128 v[188:191], v213 offset:36864
	ds_read_b128 v[192:195], v213 offset:37888
	ds_read_b128 v[196:199], v213 offset:38912
	ds_read_b128 v[200:203], v213 offset:39936
	global_load_lds_dwordx4 v178, s[28:29]
	s_mov_b32 m0, s36
	s_nop 0
	global_load_lds_dwordx4 v180, s[28:29]
	s_waitcnt vmcnt(8)
	s_waitcnt lgkmcnt(0)
	s_barrier
	v_mfma_f32_16x16x32_bf16 v[126:129], v[130:133], v[162:165], v[126:129]
	v_mfma_f32_16x16x32_bf16 v[126:129], v[134:137], v[166:169], v[126:129]
	v_mfma_f32_16x16x32_bf16 v[122:125], v[142:145], v[166:169], v[122:125]
	v_mfma_f32_16x16x32_bf16 v[122:125], v[138:141], v[162:165], v[122:125]
	v_mfma_f32_16x16x32_bf16 v[106:109], v[138:141], v[170:173], v[106:109]
	v_mfma_f32_16x16x32_bf16 v[106:109], v[142:145], v[174:177], v[106:109]
	v_mfma_f32_16x16x32_bf16 v[110:113], v[134:137], v[174:177], v[110:113]
	v_mfma_f32_16x16x32_bf16 v[110:113], v[130:133], v[170:173], v[110:113]
	v_mfma_f32_16x16x32_bf16 v[94:97], v[130:133], v[188:191], v[94:97]
	v_mfma_f32_16x16x32_bf16 v[94:97], v[134:137], v[192:195], v[94:97]
	v_mfma_f32_16x16x32_bf16 v[90:93], v[142:145], v[192:195], v[90:93]
	v_mfma_f32_16x16x32_bf16 v[90:93], v[138:141], v[188:191], v[90:93]
	v_mfma_f32_16x16x32_bf16 v[74:77], v[138:141], v[196:199], v[74:77]
	v_mfma_f32_16x16x32_bf16 v[74:77], v[142:145], v[200:203], v[74:77]
	v_mfma_f32_16x16x32_bf16 v[78:81], v[134:137], v[200:203], v[78:81]
	v_mfma_f32_16x16x32_bf16 v[78:81], v[130:133], v[196:199], v[78:81]
	v_mfma_f32_16x16x32_bf16 v[118:121], v[146:149], v[162:165], v[118:121]
	v_mfma_f32_16x16x32_bf16 v[118:121], v[150:153], v[166:169], v[118:121]
	v_mfma_f32_16x16x32_bf16 v[114:117], v[158:161], v[166:169], v[114:117]
	v_mfma_f32_16x16x32_bf16 v[114:117], v[154:157], v[162:165], v[114:117]
	v_mfma_f32_16x16x32_bf16 v[98:101], v[154:157], v[170:173], v[98:101]
	v_mfma_f32_16x16x32_bf16 v[98:101], v[158:161], v[174:177], v[98:101]
	v_mfma_f32_16x16x32_bf16 v[102:105], v[150:153], v[174:177], v[102:105]
	v_mfma_f32_16x16x32_bf16 v[102:105], v[146:149], v[170:173], v[102:105]
	v_mfma_f32_16x16x32_bf16 v[86:89], v[146:149], v[188:191], v[86:89]
	v_mfma_f32_16x16x32_bf16 v[86:89], v[150:153], v[192:195], v[86:89]
	v_mfma_f32_16x16x32_bf16 v[82:85], v[158:161], v[192:195], v[82:85]
	v_mfma_f32_16x16x32_bf16 v[82:85], v[154:157], v[188:191], v[82:85]
	v_mfma_f32_16x16x32_bf16 v[66:69], v[154:157], v[196:199], v[66:69]
	v_mfma_f32_16x16x32_bf16 v[66:69], v[158:161], v[200:203], v[66:69]
	v_mfma_f32_16x16x32_bf16 v[70:73], v[150:153], v[200:203], v[70:73]
	v_mfma_f32_16x16x32_bf16 v[70:73], v[146:149], v[196:199], v[70:73]
	s_barrier
	s_add_i32 s28, s54, s1
	v_lshl_add_u64 v[204:205], v[204:205], 0, s[34:35]
	s_mov_b32 m0, s28
	ds_read_b128 v[162:165], v213 offset:49152
	ds_read_b128 v[166:169], v213 offset:50176
	ds_read_b128 v[170:173], v213 offset:51200
	ds_read_b128 v[174:177], v213 offset:52224
	ds_read_b128 v[188:191], v213 offset:53248
	ds_read_b128 v[192:195], v213 offset:54272
	ds_read_b128 v[196:199], v213 offset:55296
	ds_read_b128 v[200:203], v213 offset:56320
	global_load_lds_dwordx4 v[204:205], off
	s_add_i32 m0, s28, 0x2000
	s_add_u32 s28, s42, 0x80080
	v_lshl_add_u64 v[204:205], v[206:207], 0, s[34:35]
	s_addc_u32 s29, s43, 0
	s_add_i32 s42, s55, s1
	global_load_lds_dwordx4 v[204:205], off
	s_mov_b32 m0, s42
	s_nop 0
	global_load_lds_dwordx4 v32, s[28:29]
	s_add_i32 m0, s42, 0x2000
	s_nop 0
	global_load_lds_dwordx4 v182, s[28:29]
	v_lshl_add_u64 v[204:205], v[208:209], 0, s[34:35]
	s_mov_b32 m0, s44
	s_nop 0
	global_load_lds_dwordx4 v[204:205], off
	v_lshl_add_u64 v[204:205], v[214:215], 0, s[34:35]
	s_mov_b32 m0, s45
	s_nop 0
	global_load_lds_dwordx4 v[204:205], off
	s_waitcnt vmcnt(8)
	s_waitcnt lgkmcnt(0)
	s_barrier
	v_mfma_f32_16x16x32_bf16 v[62:65], v[130:133], v[162:165], v[62:65]
	v_mfma_f32_16x16x32_bf16 v[62:65], v[134:137], v[166:169], v[62:65]
	v_mfma_f32_16x16x32_bf16 v[58:61], v[142:145], v[166:169], v[58:61]
	v_mfma_f32_16x16x32_bf16 v[58:61], v[138:141], v[162:165], v[58:61]
	v_mfma_f32_16x16x32_bf16 v[42:45], v[138:141], v[170:173], v[42:45]
	v_mfma_f32_16x16x32_bf16 v[42:45], v[142:145], v[174:177], v[42:45]
	v_mfma_f32_16x16x32_bf16 v[46:49], v[134:137], v[174:177], v[46:49]
	v_mfma_f32_16x16x32_bf16 v[46:49], v[130:133], v[170:173], v[46:49]
	v_mfma_f32_16x16x32_bf16 v[28:31], v[130:133], v[188:191], v[28:31]
	v_mfma_f32_16x16x32_bf16 v[28:31], v[134:137], v[192:195], v[28:31]
	v_mfma_f32_16x16x32_bf16 v[24:27], v[142:145], v[192:195], v[24:27]
	v_mfma_f32_16x16x32_bf16 v[24:27], v[138:141], v[188:191], v[24:27]
	v_mfma_f32_16x16x32_bf16 v[8:11], v[138:141], v[196:199], v[8:11]
	v_mfma_f32_16x16x32_bf16 v[8:11], v[142:145], v[200:203], v[8:11]
	v_mfma_f32_16x16x32_bf16 v[12:15], v[134:137], v[200:203], v[12:15]
	v_mfma_f32_16x16x32_bf16 v[12:15], v[130:133], v[196:199], v[12:15]
	v_mfma_f32_16x16x32_bf16 v[54:57], v[146:149], v[162:165], v[54:57]
	v_mfma_f32_16x16x32_bf16 v[54:57], v[150:153], v[166:169], v[54:57]
	v_mfma_f32_16x16x32_bf16 v[50:53], v[158:161], v[166:169], v[50:53]
	v_mfma_f32_16x16x32_bf16 v[50:53], v[154:157], v[162:165], v[50:53]
	v_mfma_f32_16x16x32_bf16 v[34:37], v[154:157], v[170:173], v[34:37]
	v_mfma_f32_16x16x32_bf16 v[34:37], v[158:161], v[174:177], v[34:37]
	v_mfma_f32_16x16x32_bf16 v[38:41], v[150:153], v[174:177], v[38:41]
	v_mfma_f32_16x16x32_bf16 v[38:41], v[146:149], v[170:173], v[38:41]
	v_mfma_f32_16x16x32_bf16 v[20:23], v[146:149], v[188:191], v[20:23]
	v_mfma_f32_16x16x32_bf16 v[20:23], v[150:153], v[192:195], v[20:23]
	v_mfma_f32_16x16x32_bf16 v[16:19], v[158:161], v[192:195], v[16:19]
	v_mfma_f32_16x16x32_bf16 v[16:19], v[154:157], v[188:191], v[16:19]
	v_mfma_f32_16x16x32_bf16 v[0:3], v[154:157], v[196:199], v[0:3]
	v_mfma_f32_16x16x32_bf16 v[0:3], v[158:161], v[200:203], v[0:3]
	v_mfma_f32_16x16x32_bf16 v[4:7], v[150:153], v[200:203], v[4:7]
	v_mfma_f32_16x16x32_bf16 v[4:7], v[146:149], v[196:199], v[4:7]
	s_barrier
	s_add_i32 s53, s53, 2
	s_add_u32 s40, s40, 0x100
	s_addc_u32 s41, s41, 0
	s_add_u32 s51, s51, 0x100
	s_addc_u32 s52, s52, 0
	s_cmp_gt_u32 s53, 29
	s_cbranch_scc0 .LBB0_120
	s_setprio 0
	s_and_b64 vcc, exec, s[18:19]
	s_cbranch_vccz .LBB0_123
	s_barrier

.LBB0_684:
	s_add_u32 s52, s40, 0x100
	s_addc_u32 s53, s41, 0
	s_ashr_i32 s23, s22, 31
	s_lshl_b64 s[30:31], s[22:23], 20
	s_add_u32 s30, s10, s30
	s_addc_u32 s31, s11, s31
	s_and_b64 s[28:29], s[28:29], exec
	s_cselect_b32 s23, s31, s41
	s_cselect_b32 s54, s30, s40
	s_add_u32 s28, s16, 0x80080
	s_addc_u32 s29, s17, 0
	v_lshl_add_u64 v[130:131], s[28:29], 0, v[176:177]
	v_lshl_add_u64 v[132:133], s[28:29], 0, v[178:179]
	s_mov_b32 s55, -2
	s_mov_b64 s[40:41], 0
	s_and_b64 vcc, exec, s[18:19]
	s_cbranch_vccnz .Lprio_skip_685
	s_setprio 1
.Lprio_skip_685:
.LBB0_685:
	s_add_u32 s28, s16, s40
	s_addc_u32 s29, s17, s41
	s_add_u32 s28, s28, 0x100
	s_addc_u32 s29, s29, 0
	s_add_u32 s42, s52, s40
	s_addc_u32 s43, s53, s41
	s_add_i32 s56, 0, 0x10000
	s_cmpk_eq_i32 s40, 0xf00
	s_cselect_b32 s29, s39, s29
	s_cselect_b32 s28, s38, s28
	s_cselect_b32 s43, s23, s43
	s_cselect_b32 s42, s54, s42
	s_add_i32 s58, 0, 0x14000
	v_add_u32_e32 v146, s56, v190
	v_add_u32_e32 v162, s58, v190
	ds_read_b128 v[134:137], v146
	ds_read_b128 v[138:141], v146 offset:1024
	ds_read_b128 v[142:145], v146 offset:2048
	ds_read_b128 v[146:149], v146 offset:3072
	ds_read_b128 v[150:153], v162
	ds_read_b128 v[154:157], v162 offset:1024
	ds_read_b128 v[158:161], v162 offset:2048
	ds_read_b128 v[162:165], v162 offset:3072
	v_lshl_add_u64 v[212:213], v[130:131], 0, s[40:41]
	s_add_i32 m0, s24, 0xc000
	ds_read_b128 v[166:169], v191
	ds_read_b128 v[180:183], v191 offset:1024
	ds_read_b128 v[184:187], v191 offset:2048
	ds_read_b128 v[192:195], v191 offset:3072
	ds_read_b128 v[196:199], v191 offset:4096
	ds_read_b128 v[200:203], v191 offset:5120
	ds_read_b128 v[204:207], v191 offset:6144
	ds_read_b128 v[208:211], v191 offset:7168
	global_load_lds_dwordx4 v[212:213], off
	v_lshl_add_u64 v[212:213], v[132:133], 0, s[40:41]
	s_add_i32 m0, s24, 0xe000
	s_nop 0
	global_load_lds_dwordx4 v[212:213], off
	s_waitcnt vmcnt(8)
	s_waitcnt lgkmcnt(0)
	s_barrier
	v_mfma_f32_16x16x32_bf16 v[82:85], v[134:137], v[166:169], v[82:85]
	v_mfma_f32_16x16x32_bf16 v[82:85], v[138:141], v[180:183], v[82:85]
	v_mfma_f32_16x16x32_bf16 v[78:81], v[146:149], v[180:183], v[78:81]
	v_mfma_f32_16x16x32_bf16 v[78:81], v[142:145], v[166:169], v[78:81]
	v_mfma_f32_16x16x32_bf16 v[70:73], v[142:145], v[184:187], v[70:73]
	v_mfma_f32_16x16x32_bf16 v[70:73], v[146:149], v[192:195], v[70:73]
	v_mfma_f32_16x16x32_bf16 v[74:77], v[138:141], v[192:195], v[74:77]
	v_mfma_f32_16x16x32_bf16 v[74:77], v[134:137], v[184:187], v[74:77]
	v_mfma_f32_16x16x32_bf16 v[66:69], v[134:137], v[196:199], v[66:69]
	v_mfma_f32_16x16x32_bf16 v[66:69], v[138:141], v[200:203], v[66:69]
	v_mfma_f32_16x16x32_bf16 v[62:65], v[146:149], v[200:203], v[62:65]
	v_mfma_f32_16x16x32_bf16 v[62:65], v[142:145], v[196:199], v[62:65]
	v_mfma_f32_16x16x32_bf16 v[54:57], v[142:145], v[204:207], v[54:57]
	v_mfma_f32_16x16x32_bf16 v[54:57], v[146:149], v[208:211], v[54:57]
	v_mfma_f32_16x16x32_bf16 v[58:61], v[138:141], v[208:211], v[58:61]
	v_mfma_f32_16x16x32_bf16 v[58:61], v[134:137], v[204:207], v[58:61]
	v_mfma_f32_16x16x32_bf16 v[50:53], v[150:153], v[166:169], v[50:53]
	v_mfma_f32_16x16x32_bf16 v[50:53], v[154:157], v[180:183], v[50:53]
	v_mfma_f32_16x16x32_bf16 v[46:49], v[162:165], v[180:183], v[46:49]
	v_mfma_f32_16x16x32_bf16 v[46:49], v[158:161], v[166:169], v[46:49]
	v_mfma_f32_16x16x32_bf16 v[38:41], v[158:161], v[184:187], v[38:41]
	v_mfma_f32_16x16x32_bf16 v[38:41], v[162:165], v[192:195], v[38:41]
	v_mfma_f32_16x16x32_bf16 v[42:45], v[154:157], v[192:195], v[42:45]
	v_mfma_f32_16x16x32_bf16 v[42:45], v[150:153], v[184:187], v[42:45]
	v_mfma_f32_16x16x32_bf16 v[34:37], v[150:153], v[196:199], v[34:37]
	v_mfma_f32_16x16x32_bf16 v[34:37], v[154:157], v[200:203], v[34:37]
	v_mfma_f32_16x16x32_bf16 v[28:31], v[162:165], v[200:203], v[28:31]
	v_mfma_f32_16x16x32_bf16 v[28:31], v[158:161], v[196:199], v[28:31]
	v_mfma_f32_16x16x32_bf16 v[20:23], v[158:161], v[204:207], v[20:23]
	v_mfma_f32_16x16x32_bf16 v[20:23], v[162:165], v[208:211], v[20:23]
	v_mfma_f32_16x16x32_bf16 v[24:27], v[154:157], v[208:211], v[24:27]
	v_mfma_f32_16x16x32_bf16 v[24:27], v[150:153], v[204:207], v[24:27]
	s_barrier
	s_add_i32 s56, s56, s13
	v_lshl_add_u64 v[212:213], s[42:43], 0, v[32:33]
	s_mov_b32 m0, s56
	ds_read_b128 v[166:169], v191 offset:16384
	ds_read_b128 v[180:183], v191 offset:17408
	ds_read_b128 v[184:187], v191 offset:18432
	ds_read_b128 v[192:195], v191 offset:19456
	ds_read_b128 v[196:199], v191 offset:20480
	ds_read_b128 v[200:203], v191 offset:21504
	ds_read_b128 v[204:207], v191 offset:22528
	ds_read_b128 v[208:211], v191 offset:23552
	global_load_lds_dwordx4 v[212:213], off
	s_add_i32 m0, s56, 0x2000
	s_add_u32 s56, s42, 0x80000
	v_lshl_add_u64 v[214:215], s[42:43], 0, v[174:175]
	s_addc_u32 s57, s43, 0
	s_add_i32 s58, s58, s13
	global_load_lds_dwordx4 v[214:215], off
	s_mov_b32 m0, s58
	v_lshl_add_u64 v[220:221], s[28:29], 0, v[172:173]
	global_load_lds_dwordx4 v32, s[56:57]
	s_add_i32 m0, s58, 0x2000
	s_nop 0
	global_load_lds_dwordx4 v174, s[56:57]
	v_lshl_add_u64 v[216:217], s[28:29], 0, v[170:171]
	s_mov_b32 m0, s24
	s_nop 0
	global_load_lds_dwordx4 v[216:217], off
	s_mov_b32 m0, s25
	s_nop 0
	global_load_lds_dwordx4 v[220:221], off
	s_waitcnt vmcnt(8)
	s_waitcnt lgkmcnt(0)
	s_barrier
	v_mfma_f32_16x16x32_bf16 v[16:19], v[134:137], v[166:169], v[16:19]
	v_mfma_f32_16x16x32_bf16 v[16:19], v[138:141], v[180:183], v[16:19]
	v_mfma_f32_16x16x32_bf16 v[12:15], v[146:149], v[180:183], v[12:15]
	v_mfma_f32_16x16x32_bf16 v[12:15], v[142:145], v[166:169], v[12:15]
	v_mfma_f32_16x16x32_bf16 v[4:7], v[142:145], v[184:187], v[4:7]
	v_mfma_f32_16x16x32_bf16 v[4:7], v[146:149], v[192:195], v[4:7]
	v_mfma_f32_16x16x32_bf16 v[8:11], v[138:141], v[192:195], v[8:11]
	v_mfma_f32_16x16x32_bf16 v[8:11], v[134:137], v[184:187], v[8:11]
	v_mfma_f32_16x16x32_bf16 v[0:3], v[134:137], v[196:199], v[0:3]
	v_mfma_f32_16x16x32_bf16 v[0:3], v[138:141], v[200:203], v[0:3]
	v_mfma_f32_16x16x32_bf16 v[86:89], v[146:149], v[200:203], v[86:89]
	v_mfma_f32_16x16x32_bf16 v[86:89], v[142:145], v[196:199], v[86:89]
	v_mfma_f32_16x16x32_bf16 v[94:97], v[142:145], v[204:207], v[94:97]
	v_mfma_f32_16x16x32_bf16 v[94:97], v[146:149], v[208:211], v[94:97]
	v_mfma_f32_16x16x32_bf16 v[90:93], v[138:141], v[208:211], v[90:93]
	v_mfma_f32_16x16x32_bf16 v[90:93], v[134:137], v[204:207], v[90:93]
	v_mfma_f32_16x16x32_bf16 v[98:101], v[150:153], v[166:169], v[98:101]
	v_mfma_f32_16x16x32_bf16 v[98:101], v[154:157], v[180:183], v[98:101]
	v_mfma_f32_16x16x32_bf16 v[102:105], v[162:165], v[180:183], v[102:105]
	v_mfma_f32_16x16x32_bf16 v[102:105], v[158:161], v[166:169], v[102:105]
	v_mfma_f32_16x16x32_bf16 v[110:113], v[158:161], v[184:187], v[110:113]
	v_mfma_f32_16x16x32_bf16 v[110:113], v[162:165], v[192:195], v[110:113]
	v_mfma_f32_16x16x32_bf16 v[106:109], v[154:157], v[192:195], v[106:109]
	v_mfma_f32_16x16x32_bf16 v[106:109], v[150:153], v[184:187], v[106:109]
	v_mfma_f32_16x16x32_bf16 v[114:117], v[150:153], v[196:199], v[114:117]
	v_mfma_f32_16x16x32_bf16 v[114:117], v[154:157], v[200:203], v[114:117]
	v_mfma_f32_16x16x32_bf16 v[118:121], v[162:165], v[200:203], v[118:121]
	v_mfma_f32_16x16x32_bf16 v[118:121], v[158:161], v[196:199], v[118:121]
	v_mfma_f32_16x16x32_bf16 v[126:129], v[158:161], v[204:207], v[126:129]
	v_mfma_f32_16x16x32_bf16 v[126:129], v[162:165], v[208:211], v[126:129]
	v_mfma_f32_16x16x32_bf16 v[122:125], v[154:157], v[208:211], v[122:125]
	v_mfma_f32_16x16x32_bf16 v[122:125], v[150:153], v[204:207], v[122:125]
	s_barrier
	s_add_i32 s56, 0, 0x18000
	s_add_i32 s57, 0, 0x1c000
	v_add_u32_e32 v146, s56, v190
	v_add_u32_e32 v162, s57, v190
	ds_read_b128 v[134:137], v146
	ds_read_b128 v[138:141], v146 offset:1024
	ds_read_b128 v[142:145], v146 offset:2048
	ds_read_b128 v[146:149], v146 offset:3072
	ds_read_b128 v[150:153], v162
	ds_read_b128 v[154:157], v162 offset:1024
	ds_read_b128 v[158:161], v162 offset:2048
	ds_read_b128 v[162:165], v162 offset:3072
	s_add_u32 s28, s28, 0x80000
	s_addc_u32 s29, s29, 0
	s_mov_b32 m0, s33
	ds_read_b128 v[166:169], v191 offset:32768
	ds_read_b128 v[180:183], v191 offset:33792
	ds_read_b128 v[184:187], v191 offset:34816
	ds_read_b128 v[192:195], v191 offset:35840
	ds_read_b128 v[196:199], v191 offset:36864
	ds_read_b128 v[200:203], v191 offset:37888
	ds_read_b128 v[204:207], v191 offset:38912
	ds_read_b128 v[208:211], v191 offset:39936
	global_load_lds_dwordx4 v170, s[28:29]
	s_mov_b32 m0, s36
	s_nop 0
	global_load_lds_dwordx4 v172, s[28:29]
	s_waitcnt vmcnt(8)
	s_waitcnt lgkmcnt(0)
	s_barrier
	v_mfma_f32_16x16x32_bf16 v[82:85], v[134:137], v[166:169], v[82:85]
	v_mfma_f32_16x16x32_bf16 v[82:85], v[138:141], v[180:183], v[82:85]
	v_mfma_f32_16x16x32_bf16 v[78:81], v[146:149], v[180:183], v[78:81]
	v_mfma_f32_16x16x32_bf16 v[78:81], v[142:145], v[166:169], v[78:81]
	v_mfma_f32_16x16x32_bf16 v[70:73], v[142:145], v[184:187], v[70:73]
	v_mfma_f32_16x16x32_bf16 v[70:73], v[146:149], v[192:195], v[70:73]
	v_mfma_f32_16x16x32_bf16 v[74:77], v[138:141], v[192:195], v[74:77]
	v_mfma_f32_16x16x32_bf16 v[74:77], v[134:137], v[184:187], v[74:77]
	v_mfma_f32_16x16x32_bf16 v[66:69], v[134:137], v[196:199], v[66:69]
	v_mfma_f32_16x16x32_bf16 v[66:69], v[138:141], v[200:203], v[66:69]
	v_mfma_f32_16x16x32_bf16 v[62:65], v[146:149], v[200:203], v[62:65]
	v_mfma_f32_16x16x32_bf16 v[62:65], v[142:145], v[196:199], v[62:65]
	v_mfma_f32_16x16x32_bf16 v[54:57], v[142:145], v[204:207], v[54:57]
	v_mfma_f32_16x16x32_bf16 v[54:57], v[146:149], v[208:211], v[54:57]
	v_mfma_f32_16x16x32_bf16 v[58:61], v[138:141], v[208:211], v[58:61]
	v_mfma_f32_16x16x32_bf16 v[58:61], v[134:137], v[204:207], v[58:61]
	v_mfma_f32_16x16x32_bf16 v[50:53], v[150:153], v[166:169], v[50:53]
	v_mfma_f32_16x16x32_bf16 v[50:53], v[154:157], v[180:183], v[50:53]
	v_mfma_f32_16x16x32_bf16 v[46:49], v[162:165], v[180:183], v[46:49]
	v_mfma_f32_16x16x32_bf16 v[46:49], v[158:161], v[166:169], v[46:49]
	v_mfma_f32_16x16x32_bf16 v[38:41], v[158:161], v[184:187], v[38:41]
	v_mfma_f32_16x16x32_bf16 v[38:41], v[162:165], v[192:195], v[38:41]
	v_mfma_f32_16x16x32_bf16 v[42:45], v[154:157], v[192:195], v[42:45]
	v_mfma_f32_16x16x32_bf16 v[42:45], v[150:153], v[184:187], v[42:45]
	v_mfma_f32_16x16x32_bf16 v[34:37], v[150:153], v[196:199], v[34:37]
	v_mfma_f32_16x16x32_bf16 v[34:37], v[154:157], v[200:203], v[34:37]
	v_mfma_f32_16x16x32_bf16 v[28:31], v[162:165], v[200:203], v[28:31]
	v_mfma_f32_16x16x32_bf16 v[28:31], v[158:161], v[196:199], v[28:31]
	v_mfma_f32_16x16x32_bf16 v[20:23], v[158:161], v[204:207], v[20:23]
	v_mfma_f32_16x16x32_bf16 v[20:23], v[162:165], v[208:211], v[20:23]
	v_mfma_f32_16x16x32_bf16 v[24:27], v[154:157], v[208:211], v[24:27]
	v_mfma_f32_16x16x32_bf16 v[24:27], v[150:153], v[204:207], v[24:27]
	s_barrier
	s_add_i32 s28, s56, s13
	v_lshl_add_u64 v[212:213], v[212:213], 0, s[34:35]
	s_mov_b32 m0, s28
	ds_read_b128 v[166:169], v191 offset:49152
	ds_read_b128 v[180:183], v191 offset:50176
	ds_read_b128 v[184:187], v191 offset:51200
	ds_read_b128 v[192:195], v191 offset:52224
	ds_read_b128 v[196:199], v191 offset:53248
	ds_read_b128 v[200:203], v191 offset:54272
	ds_read_b128 v[204:207], v191 offset:55296
	ds_read_b128 v[208:211], v191 offset:56320
	global_load_lds_dwordx4 v[212:213], off
	s_add_i32 m0, s28, 0x2000
	s_add_u32 s28, s42, 0x80080
	v_lshl_add_u64 v[212:213], v[214:215], 0, s[34:35]
	s_addc_u32 s29, s43, 0
	s_add_i32 s42, s57, s13
	global_load_lds_dwordx4 v[212:213], off
	s_mov_b32 m0, s42
	s_nop 0
	global_load_lds_dwordx4 v32, s[28:29]
	s_add_i32 m0, s42, 0x2000
	s_nop 0
	global_load_lds_dwordx4 v174, s[28:29]
	v_lshl_add_u64 v[212:213], v[216:217], 0, s[34:35]
	s_mov_b32 m0, s45
	s_nop 0
	global_load_lds_dwordx4 v[212:213], off
	v_lshl_add_u64 v[212:213], v[220:221], 0, s[34:35]
	s_mov_b32 m0, s46
	s_nop 0
	global_load_lds_dwordx4 v[212:213], off
	s_waitcnt vmcnt(8)
	s_waitcnt lgkmcnt(0)
	s_barrier
	v_mfma_f32_16x16x32_bf16 v[16:19], v[134:137], v[166:169], v[16:19]
	v_mfma_f32_16x16x32_bf16 v[16:19], v[138:141], v[180:183], v[16:19]
	v_mfma_f32_16x16x32_bf16 v[12:15], v[146:149], v[180:183], v[12:15]
	v_mfma_f32_16x16x32_bf16 v[12:15], v[142:145], v[166:169], v[12:15]
	v_mfma_f32_16x16x32_bf16 v[4:7], v[142:145], v[184:187], v[4:7]
	v_mfma_f32_16x16x32_bf16 v[4:7], v[146:149], v[192:195], v[4:7]
	v_mfma_f32_16x16x32_bf16 v[8:11], v[138:141], v[192:195], v[8:11]
	v_mfma_f32_16x16x32_bf16 v[8:11], v[134:137], v[184:187], v[8:11]
	v_mfma_f32_16x16x32_bf16 v[0:3], v[134:137], v[196:199], v[0:3]
	v_mfma_f32_16x16x32_bf16 v[0:3], v[138:141], v[200:203], v[0:3]
	v_mfma_f32_16x16x32_bf16 v[86:89], v[146:149], v[200:203], v[86:89]
	v_mfma_f32_16x16x32_bf16 v[86:89], v[142:145], v[196:199], v[86:89]
	v_mfma_f32_16x16x32_bf16 v[94:97], v[142:145], v[204:207], v[94:97]
	v_mfma_f32_16x16x32_bf16 v[94:97], v[146:149], v[208:211], v[94:97]
	v_mfma_f32_16x16x32_bf16 v[90:93], v[138:141], v[208:211], v[90:93]
	v_mfma_f32_16x16x32_bf16 v[90:93], v[134:137], v[204:207], v[90:93]
	v_mfma_f32_16x16x32_bf16 v[98:101], v[150:153], v[166:169], v[98:101]
	v_mfma_f32_16x16x32_bf16 v[98:101], v[154:157], v[180:183], v[98:101]
	v_mfma_f32_16x16x32_bf16 v[102:105], v[162:165], v[180:183], v[102:105]
	v_mfma_f32_16x16x32_bf16 v[102:105], v[158:161], v[166:169], v[102:105]
	v_mfma_f32_16x16x32_bf16 v[110:113], v[158:161], v[184:187], v[110:113]
	v_mfma_f32_16x16x32_bf16 v[110:113], v[162:165], v[192:195], v[110:113]
	v_mfma_f32_16x16x32_bf16 v[106:109], v[154:157], v[192:195], v[106:109]
	v_mfma_f32_16x16x32_bf16 v[106:109], v[150:153], v[184:187], v[106:109]
	v_mfma_f32_16x16x32_bf16 v[114:117], v[150:153], v[196:199], v[114:117]
	v_mfma_f32_16x16x32_bf16 v[114:117], v[154:157], v[200:203], v[114:117]
	v_mfma_f32_16x16x32_bf16 v[118:121], v[162:165], v[200:203], v[118:121]
	v_mfma_f32_16x16x32_bf16 v[118:121], v[158:161], v[196:199], v[118:121]
	v_mfma_f32_16x16x32_bf16 v[126:129], v[158:161], v[204:207], v[126:129]
	v_mfma_f32_16x16x32_bf16 v[126:129], v[162:165], v[208:211], v[126:129]
	v_mfma_f32_16x16x32_bf16 v[122:125], v[154:157], v[208:211], v[122:125]
	v_mfma_f32_16x16x32_bf16 v[122:125], v[150:153], v[204:207], v[122:125]
	s_barrier
	s_add_i32 s55, s55, 2
	s_add_u32 s40, s40, 0x100
	s_addc_u32 s41, s41, 0
	s_cmp_gt_u32 s55, 29
	s_cbranch_scc0 .LBB0_685
	s_setprio 0
	s_and_b64 vcc, exec, s[18:19]
	s_cbranch_vccz .LBB0_688
	s_barrier

.LBB0_754:
	s_add_u32 s33, s6, 0x100
	v_mov_b32_e32 v0, 0
	s_addc_u32 s50, s7, 0
	s_mov_b32 s51, -2
	s_waitcnt lgkmcnt(0)
	v_mov_b32_e32 v1, v0
	v_mov_b32_e32 v2, v0
	v_mov_b32_e32 v3, v0
	v_mov_b32_e32 v4, v0
	v_mov_b32_e32 v5, v0
	v_mov_b32_e32 v6, v0
	v_mov_b32_e32 v7, v0
	v_mov_b32_e32 v16, v0
	v_mov_b32_e32 v17, v0
	v_mov_b32_e32 v18, v0
	v_mov_b32_e32 v19, v0
	v_mov_b32_e32 v20, v0
	v_mov_b32_e32 v21, v0
	v_mov_b32_e32 v22, v0
	v_mov_b32_e32 v23, v0
	s_waitcnt vmcnt(0)
	v_mov_b32_e32 v34, v0
	v_mov_b32_e32 v35, v0
	v_mov_b32_e32 v36, v0
	v_mov_b32_e32 v37, v0
	v_mov_b32_e32 v38, v0
	v_mov_b32_e32 v39, v0
	v_mov_b32_e32 v40, v0
	v_mov_b32_e32 v41, v0
	v_mov_b32_e32 v50, v0
	v_mov_b32_e32 v51, v0
	v_mov_b32_e32 v52, v0
	v_mov_b32_e32 v53, v0
	v_mov_b32_e32 v54, v0
	v_mov_b32_e32 v55, v0
	v_mov_b32_e32 v56, v0
	v_mov_b32_e32 v57, v0
	v_mov_b32_e32 v8, v0
	v_mov_b32_e32 v9, v0
	v_mov_b32_e32 v10, v0
	v_mov_b32_e32 v11, v0
	v_mov_b32_e32 v12, v0
	v_mov_b32_e32 v13, v0
	v_mov_b32_e32 v14, v0
	v_mov_b32_e32 v15, v0
	v_mov_b32_e32 v24, v0
	v_mov_b32_e32 v25, v0
	v_mov_b32_e32 v26, v0
	v_mov_b32_e32 v27, v0
	v_mov_b32_e32 v28, v0
	v_mov_b32_e32 v29, v0
	v_mov_b32_e32 v30, v0
	v_mov_b32_e32 v31, v0
	v_mov_b32_e32 v42, v0
	v_mov_b32_e32 v43, v0
	v_mov_b32_e32 v44, v0
	v_mov_b32_e32 v45, v0
	v_mov_b32_e32 v46, v0
	v_mov_b32_e32 v47, v0
	v_mov_b32_e32 v48, v0
	v_mov_b32_e32 v49, v0
	v_mov_b32_e32 v58, v0
	v_mov_b32_e32 v59, v0
	v_mov_b32_e32 v60, v0
	v_mov_b32_e32 v61, v0
	v_mov_b32_e32 v62, v0
	v_mov_b32_e32 v63, v0
	v_mov_b32_e32 v64, v0
	v_mov_b32_e32 v65, v0
	v_mov_b32_e32 v66, v0
	v_mov_b32_e32 v67, v0
	v_mov_b32_e32 v68, v0
	v_mov_b32_e32 v69, v0
	v_mov_b32_e32 v70, v0
	v_mov_b32_e32 v71, v0
	v_mov_b32_e32 v72, v0
	v_mov_b32_e32 v73, v0
	v_mov_b32_e32 v82, v0
	v_mov_b32_e32 v83, v0
	v_mov_b32_e32 v84, v0
	v_mov_b32_e32 v85, v0
	v_mov_b32_e32 v86, v0
	v_mov_b32_e32 v87, v0
	v_mov_b32_e32 v88, v0
	v_mov_b32_e32 v89, v0
	v_mov_b32_e32 v98, v0
	v_mov_b32_e32 v99, v0
	v_mov_b32_e32 v100, v0
	v_mov_b32_e32 v101, v0
	v_mov_b32_e32 v102, v0
	v_mov_b32_e32 v103, v0
	v_mov_b32_e32 v104, v0
	v_mov_b32_e32 v105, v0
	v_mov_b32_e32 v114, v0
	v_mov_b32_e32 v115, v0
	v_mov_b32_e32 v116, v0
	v_mov_b32_e32 v117, v0
	v_mov_b32_e32 v118, v0
	v_mov_b32_e32 v119, v0
	v_mov_b32_e32 v120, v0
	v_mov_b32_e32 v121, v0
	v_mov_b32_e32 v74, v0
	v_mov_b32_e32 v75, v0
	v_mov_b32_e32 v76, v0
	v_mov_b32_e32 v77, v0
	v_mov_b32_e32 v78, v0
	v_mov_b32_e32 v79, v0
	v_mov_b32_e32 v80, v0
	v_mov_b32_e32 v81, v0
	v_mov_b32_e32 v90, v0
	v_mov_b32_e32 v91, v0
	v_mov_b32_e32 v92, v0
	v_mov_b32_e32 v93, v0
	v_mov_b32_e32 v94, v0
	v_mov_b32_e32 v95, v0
	v_mov_b32_e32 v96, v0
	v_mov_b32_e32 v97, v0
	v_mov_b32_e32 v106, v0
	v_mov_b32_e32 v107, v0
	v_mov_b32_e32 v108, v0
	v_mov_b32_e32 v109, v0
	v_mov_b32_e32 v110, v0
	v_mov_b32_e32 v111, v0
	v_mov_b32_e32 v112, v0
	v_mov_b32_e32 v113, v0
	v_mov_b32_e32 v122, v0
	v_mov_b32_e32 v123, v0
	v_mov_b32_e32 v124, v0
	v_mov_b32_e32 v125, v0
	v_mov_b32_e32 v126, v0
	v_mov_b32_e32 v127, v0
	v_mov_b32_e32 v128, v0
	v_mov_b32_e32 v129, v0
	s_and_b64 vcc, exec, s[18:19]
	s_cbranch_vccnz .Lprio_skip_755
	s_setprio 1
.Lprio_skip_755:
.LBB0_755:
	s_add_u32 s6, s4, 0x100
	s_addc_u32 s7, s5, 0
	s_add_i32 s52, 0, 0x10000
	s_cmpk_eq_i32 s51, 0x54
	s_cselect_b32 s29, s23, s7
	s_cselect_b32 s28, s22, s6
	s_cselect_b32 s31, s27, s50
	s_cselect_b32 s30, s26, s33
	s_add_i32 s53, 0, 0x14000
	v_add_u32_e32 v142, s52, v242
	v_add_u32_e32 v158, s53, v242
	ds_read_b128 v[130:133], v142
	ds_read_b128 v[134:137], v142 offset:1024
	ds_read_b128 v[138:141], v142 offset:2048
	ds_read_b128 v[142:145], v142 offset:3072
	ds_read_b128 v[146:149], v158
	ds_read_b128 v[150:153], v158 offset:1024
	ds_read_b128 v[154:157], v158 offset:2048
	ds_read_b128 v[158:161], v158 offset:3072
	s_add_i32 m0, s36, 0xc000
	ds_read_b128 v[162:165], v243
	ds_read_b128 v[166:169], v243 offset:1024
	ds_read_b128 v[170:173], v243 offset:2048
	ds_read_b128 v[174:177], v243 offset:3072
	ds_read_b128 v[178:181], v243 offset:4096
	ds_read_b128 v[182:185], v243 offset:5120
	ds_read_b128 v[186:189], v243 offset:6144
	ds_read_b128 v[190:193], v243 offset:7168
	global_load_lds_dwordx4 v202, s[4:5]
	s_add_i32 m0, s36, 0xe000
	s_nop 0
	global_load_lds_dwordx4 v204, s[4:5]
	s_waitcnt vmcnt(8)
	s_waitcnt lgkmcnt(0)
	s_barrier
	v_mfma_f32_16x16x32_bf16 v[126:129], v[130:133], v[162:165], v[126:129]
	v_mfma_f32_16x16x32_bf16 v[126:129], v[134:137], v[166:169], v[126:129]
	v_mfma_f32_16x16x32_bf16 v[122:125], v[142:145], v[166:169], v[122:125]
	v_mfma_f32_16x16x32_bf16 v[122:125], v[138:141], v[162:165], v[122:125]
	v_mfma_f32_16x16x32_bf16 v[106:109], v[138:141], v[170:173], v[106:109]
	v_mfma_f32_16x16x32_bf16 v[106:109], v[142:145], v[174:177], v[106:109]
	v_mfma_f32_16x16x32_bf16 v[110:113], v[134:137], v[174:177], v[110:113]
	v_mfma_f32_16x16x32_bf16 v[110:113], v[130:133], v[170:173], v[110:113]
	v_mfma_f32_16x16x32_bf16 v[94:97], v[130:133], v[178:181], v[94:97]
	v_mfma_f32_16x16x32_bf16 v[94:97], v[134:137], v[182:185], v[94:97]
	v_mfma_f32_16x16x32_bf16 v[90:93], v[142:145], v[182:185], v[90:93]
	v_mfma_f32_16x16x32_bf16 v[90:93], v[138:141], v[178:181], v[90:93]
	v_mfma_f32_16x16x32_bf16 v[74:77], v[138:141], v[186:189], v[74:77]
	v_mfma_f32_16x16x32_bf16 v[74:77], v[142:145], v[190:193], v[74:77]
	v_mfma_f32_16x16x32_bf16 v[78:81], v[134:137], v[190:193], v[78:81]
	v_mfma_f32_16x16x32_bf16 v[78:81], v[130:133], v[186:189], v[78:81]
	v_mfma_f32_16x16x32_bf16 v[118:121], v[146:149], v[162:165], v[118:121]
	v_mfma_f32_16x16x32_bf16 v[118:121], v[150:153], v[166:169], v[118:121]
	v_mfma_f32_16x16x32_bf16 v[114:117], v[158:161], v[166:169], v[114:117]
	v_mfma_f32_16x16x32_bf16 v[114:117], v[154:157], v[162:165], v[114:117]
	v_mfma_f32_16x16x32_bf16 v[98:101], v[154:157], v[170:173], v[98:101]
	v_mfma_f32_16x16x32_bf16 v[98:101], v[158:161], v[174:177], v[98:101]
	v_mfma_f32_16x16x32_bf16 v[102:105], v[150:153], v[174:177], v[102:105]
	v_mfma_f32_16x16x32_bf16 v[102:105], v[146:149], v[170:173], v[102:105]
	v_mfma_f32_16x16x32_bf16 v[86:89], v[146:149], v[178:181], v[86:89]
	v_mfma_f32_16x16x32_bf16 v[86:89], v[150:153], v[182:185], v[86:89]
	v_mfma_f32_16x16x32_bf16 v[82:85], v[158:161], v[182:185], v[82:85]
	v_mfma_f32_16x16x32_bf16 v[82:85], v[154:157], v[178:181], v[82:85]
	v_mfma_f32_16x16x32_bf16 v[66:69], v[154:157], v[186:189], v[66:69]
	v_mfma_f32_16x16x32_bf16 v[66:69], v[158:161], v[190:193], v[66:69]
	v_mfma_f32_16x16x32_bf16 v[70:73], v[150:153], v[190:193], v[70:73]
	v_mfma_f32_16x16x32_bf16 v[70:73], v[146:149], v[186:189], v[70:73]
	s_barrier
	s_add_i32 s4, s52, s1
	v_lshl_add_u64 v[194:195], s[30:31], 0, v[32:33]
	s_mov_b32 m0, s4
	ds_read_b128 v[162:165], v243 offset:16384
	ds_read_b128 v[166:169], v243 offset:17408
	ds_read_b128 v[170:173], v243 offset:18432
	ds_read_b128 v[174:177], v243 offset:19456
	ds_read_b128 v[178:181], v243 offset:20480
	ds_read_b128 v[182:185], v243 offset:21504
	ds_read_b128 v[186:189], v243 offset:22528
	ds_read_b128 v[190:193], v243 offset:23552
	global_load_lds_dwordx4 v[194:195], off
	s_add_i32 m0, s4, 0x2000
	s_add_u32 s4, s30, 0x160000
	v_lshl_add_u64 v[206:207], s[30:31], 0, v[200:201]
	s_addc_u32 s5, s31, 0
	s_add_i32 s52, s53, s1
	global_load_lds_dwordx4 v[206:207], off
	s_mov_b32 m0, s52
	v_lshl_add_u64 v[210:211], s[28:29], 0, v[198:199]
	global_load_lds_dwordx4 v32, s[4:5]
	s_add_i32 m0, s52, 0x2000
	s_nop 0
	global_load_lds_dwordx4 v200, s[4:5]
	v_lshl_add_u64 v[208:209], s[28:29], 0, v[196:197]
	s_mov_b32 m0, s36
	s_nop 0
	global_load_lds_dwordx4 v[208:209], off
	s_mov_b32 m0, s38
	s_nop 0
	global_load_lds_dwordx4 v[210:211], off
	s_waitcnt vmcnt(8)
	s_waitcnt lgkmcnt(0)
	s_barrier
	v_mfma_f32_16x16x32_bf16 v[62:65], v[130:133], v[162:165], v[62:65]
	v_mfma_f32_16x16x32_bf16 v[62:65], v[134:137], v[166:169], v[62:65]
	v_mfma_f32_16x16x32_bf16 v[58:61], v[142:145], v[166:169], v[58:61]
	v_mfma_f32_16x16x32_bf16 v[58:61], v[138:141], v[162:165], v[58:61]
	v_mfma_f32_16x16x32_bf16 v[42:45], v[138:141], v[170:173], v[42:45]
	v_mfma_f32_16x16x32_bf16 v[42:45], v[142:145], v[174:177], v[42:45]
	v_mfma_f32_16x16x32_bf16 v[46:49], v[134:137], v[174:177], v[46:49]
	v_mfma_f32_16x16x32_bf16 v[46:49], v[130:133], v[170:173], v[46:49]
	v_mfma_f32_16x16x32_bf16 v[28:31], v[130:133], v[178:181], v[28:31]
	v_mfma_f32_16x16x32_bf16 v[28:31], v[134:137], v[182:185], v[28:31]
	v_mfma_f32_16x16x32_bf16 v[24:27], v[142:145], v[182:185], v[24:27]
	v_mfma_f32_16x16x32_bf16 v[24:27], v[138:141], v[178:181], v[24:27]
	v_mfma_f32_16x16x32_bf16 v[8:11], v[138:141], v[186:189], v[8:11]
	v_mfma_f32_16x16x32_bf16 v[8:11], v[142:145], v[190:193], v[8:11]
	v_mfma_f32_16x16x32_bf16 v[12:15], v[134:137], v[190:193], v[12:15]
	v_mfma_f32_16x16x32_bf16 v[12:15], v[130:133], v[186:189], v[12:15]
	v_mfma_f32_16x16x32_bf16 v[54:57], v[146:149], v[162:165], v[54:57]
	v_mfma_f32_16x16x32_bf16 v[54:57], v[150:153], v[166:169], v[54:57]
	v_mfma_f32_16x16x32_bf16 v[50:53], v[158:161], v[166:169], v[50:53]
	v_mfma_f32_16x16x32_bf16 v[50:53], v[154:157], v[162:165], v[50:53]
	v_mfma_f32_16x16x32_bf16 v[34:37], v[154:157], v[170:173], v[34:37]
	v_mfma_f32_16x16x32_bf16 v[34:37], v[158:161], v[174:177], v[34:37]
	v_mfma_f32_16x16x32_bf16 v[38:41], v[150:153], v[174:177], v[38:41]
	v_mfma_f32_16x16x32_bf16 v[38:41], v[146:149], v[170:173], v[38:41]
	v_mfma_f32_16x16x32_bf16 v[20:23], v[146:149], v[178:181], v[20:23]
	v_mfma_f32_16x16x32_bf16 v[20:23], v[150:153], v[182:185], v[20:23]
	v_mfma_f32_16x16x32_bf16 v[16:19], v[158:161], v[182:185], v[16:19]
	v_mfma_f32_16x16x32_bf16 v[16:19], v[154:157], v[178:181], v[16:19]
	v_mfma_f32_16x16x32_bf16 v[0:3], v[154:157], v[186:189], v[0:3]
	v_mfma_f32_16x16x32_bf16 v[0:3], v[158:161], v[190:193], v[0:3]
	v_mfma_f32_16x16x32_bf16 v[4:7], v[150:153], v[190:193], v[4:7]
	v_mfma_f32_16x16x32_bf16 v[4:7], v[146:149], v[186:189], v[4:7]
	s_barrier
	s_add_i32 s52, 0, 0x18000
	s_add_i32 s53, 0, 0x1c000
	v_add_u32_e32 v142, s52, v242
	v_add_u32_e32 v158, s53, v242
	ds_read_b128 v[130:133], v142
	ds_read_b128 v[134:137], v142 offset:1024
	ds_read_b128 v[138:141], v142 offset:2048
	ds_read_b128 v[142:145], v142 offset:3072
	ds_read_b128 v[146:149], v158
	ds_read_b128 v[150:153], v158 offset:1024
	ds_read_b128 v[154:157], v158 offset:2048
	ds_read_b128 v[158:161], v158 offset:3072
	s_add_u32 s4, s28, 0x160000
	s_addc_u32 s5, s29, 0
	s_mov_b32 m0, s39
	ds_read_b128 v[162:165], v243 offset:32768
	ds_read_b128 v[166:169], v243 offset:33792
	ds_read_b128 v[170:173], v243 offset:34816
	ds_read_b128 v[174:177], v243 offset:35840
	ds_read_b128 v[178:181], v243 offset:36864
	ds_read_b128 v[182:185], v243 offset:37888
	ds_read_b128 v[186:189], v243 offset:38912
	ds_read_b128 v[190:193], v243 offset:39936
	global_load_lds_dwordx4 v196, s[4:5]
	s_mov_b32 m0, s42
	s_nop 0
	global_load_lds_dwordx4 v198, s[4:5]
	s_waitcnt vmcnt(8)
	s_waitcnt lgkmcnt(0)
	s_barrier
	v_mfma_f32_16x16x32_bf16 v[126:129], v[130:133], v[162:165], v[126:129]
	v_mfma_f32_16x16x32_bf16 v[126:129], v[134:137], v[166:169], v[126:129]
	v_mfma_f32_16x16x32_bf16 v[122:125], v[142:145], v[166:169], v[122:125]
	v_mfma_f32_16x16x32_bf16 v[122:125], v[138:141], v[162:165], v[122:125]
	v_mfma_f32_16x16x32_bf16 v[106:109], v[138:141], v[170:173], v[106:109]
	v_mfma_f32_16x16x32_bf16 v[106:109], v[142:145], v[174:177], v[106:109]
	v_mfma_f32_16x16x32_bf16 v[110:113], v[134:137], v[174:177], v[110:113]
	v_mfma_f32_16x16x32_bf16 v[110:113], v[130:133], v[170:173], v[110:113]
	v_mfma_f32_16x16x32_bf16 v[94:97], v[130:133], v[178:181], v[94:97]
	v_mfma_f32_16x16x32_bf16 v[94:97], v[134:137], v[182:185], v[94:97]
	v_mfma_f32_16x16x32_bf16 v[90:93], v[142:145], v[182:185], v[90:93]
	v_mfma_f32_16x16x32_bf16 v[90:93], v[138:141], v[178:181], v[90:93]
	v_mfma_f32_16x16x32_bf16 v[74:77], v[138:141], v[186:189], v[74:77]
	v_mfma_f32_16x16x32_bf16 v[74:77], v[142:145], v[190:193], v[74:77]
	v_mfma_f32_16x16x32_bf16 v[78:81], v[134:137], v[190:193], v[78:81]
	v_mfma_f32_16x16x32_bf16 v[78:81], v[130:133], v[186:189], v[78:81]
	v_mfma_f32_16x16x32_bf16 v[118:121], v[146:149], v[162:165], v[118:121]
	v_mfma_f32_16x16x32_bf16 v[118:121], v[150:153], v[166:169], v[118:121]
	v_mfma_f32_16x16x32_bf16 v[114:117], v[158:161], v[166:169], v[114:117]
	v_mfma_f32_16x16x32_bf16 v[114:117], v[154:157], v[162:165], v[114:117]
	v_mfma_f32_16x16x32_bf16 v[98:101], v[154:157], v[170:173], v[98:101]
	v_mfma_f32_16x16x32_bf16 v[98:101], v[158:161], v[174:177], v[98:101]
	v_mfma_f32_16x16x32_bf16 v[102:105], v[150:153], v[174:177], v[102:105]
	v_mfma_f32_16x16x32_bf16 v[102:105], v[146:149], v[170:173], v[102:105]
	v_mfma_f32_16x16x32_bf16 v[86:89], v[146:149], v[178:181], v[86:89]
	v_mfma_f32_16x16x32_bf16 v[86:89], v[150:153], v[182:185], v[86:89]
	v_mfma_f32_16x16x32_bf16 v[82:85], v[158:161], v[182:185], v[82:85]
	v_mfma_f32_16x16x32_bf16 v[82:85], v[154:157], v[178:181], v[82:85]
	v_mfma_f32_16x16x32_bf16 v[66:69], v[154:157], v[186:189], v[66:69]
	v_mfma_f32_16x16x32_bf16 v[66:69], v[158:161], v[190:193], v[66:69]
	v_mfma_f32_16x16x32_bf16 v[70:73], v[150:153], v[190:193], v[70:73]
	v_mfma_f32_16x16x32_bf16 v[70:73], v[146:149], v[186:189], v[70:73]
	s_barrier
	s_add_i32 s4, s52, s1
	v_lshl_add_u64 v[194:195], v[194:195], 0, s[34:35]
	s_mov_b32 m0, s4
	ds_read_b128 v[162:165], v243 offset:49152
	ds_read_b128 v[166:169], v243 offset:50176
	ds_read_b128 v[170:173], v243 offset:51200
	ds_read_b128 v[174:177], v243 offset:52224
	ds_read_b128 v[178:181], v243 offset:53248
	ds_read_b128 v[182:185], v243 offset:54272
	ds_read_b128 v[186:189], v243 offset:55296
	ds_read_b128 v[190:193], v243 offset:56320
	global_load_lds_dwordx4 v[194:195], off
	s_add_i32 m0, s4, 0x2000
	s_add_u32 s4, s30, 0x160080
	v_lshl_add_u64 v[194:195], v[206:207], 0, s[34:35]
	s_addc_u32 s5, s31, 0
	s_add_i32 s28, s53, s1
	global_load_lds_dwordx4 v[194:195], off
	s_mov_b32 m0, s28
	s_nop 0
	global_load_lds_dwordx4 v32, s[4:5]
	s_add_i32 m0, s28, 0x2000
	s_nop 0
	global_load_lds_dwordx4 v200, s[4:5]
	v_lshl_add_u64 v[194:195], v[208:209], 0, s[34:35]
	s_mov_b32 m0, s44
	s_nop 0
	global_load_lds_dwordx4 v[194:195], off
	v_lshl_add_u64 v[194:195], v[210:211], 0, s[34:35]
	s_mov_b32 m0, s45
	s_nop 0
	global_load_lds_dwordx4 v[194:195], off
	s_waitcnt vmcnt(8)
	s_waitcnt lgkmcnt(0)
	s_barrier
	v_mfma_f32_16x16x32_bf16 v[62:65], v[130:133], v[162:165], v[62:65]
	v_mfma_f32_16x16x32_bf16 v[62:65], v[134:137], v[166:169], v[62:65]
	v_mfma_f32_16x16x32_bf16 v[58:61], v[142:145], v[166:169], v[58:61]
	v_mfma_f32_16x16x32_bf16 v[58:61], v[138:141], v[162:165], v[58:61]
	v_mfma_f32_16x16x32_bf16 v[42:45], v[138:141], v[170:173], v[42:45]
	v_mfma_f32_16x16x32_bf16 v[42:45], v[142:145], v[174:177], v[42:45]
	v_mfma_f32_16x16x32_bf16 v[46:49], v[134:137], v[174:177], v[46:49]
	v_mfma_f32_16x16x32_bf16 v[46:49], v[130:133], v[170:173], v[46:49]
	v_mfma_f32_16x16x32_bf16 v[28:31], v[130:133], v[178:181], v[28:31]
	v_mfma_f32_16x16x32_bf16 v[28:31], v[134:137], v[182:185], v[28:31]
	v_mfma_f32_16x16x32_bf16 v[24:27], v[142:145], v[182:185], v[24:27]
	v_mfma_f32_16x16x32_bf16 v[24:27], v[138:141], v[178:181], v[24:27]
	v_mfma_f32_16x16x32_bf16 v[8:11], v[138:141], v[186:189], v[8:11]
	v_mfma_f32_16x16x32_bf16 v[8:11], v[142:145], v[190:193], v[8:11]
	v_mfma_f32_16x16x32_bf16 v[12:15], v[134:137], v[190:193], v[12:15]
	v_mfma_f32_16x16x32_bf16 v[12:15], v[130:133], v[186:189], v[12:15]
	v_mfma_f32_16x16x32_bf16 v[54:57], v[146:149], v[162:165], v[54:57]
	v_mfma_f32_16x16x32_bf16 v[54:57], v[150:153], v[166:169], v[54:57]
	v_mfma_f32_16x16x32_bf16 v[50:53], v[158:161], v[166:169], v[50:53]
	v_mfma_f32_16x16x32_bf16 v[50:53], v[154:157], v[162:165], v[50:53]
	v_mfma_f32_16x16x32_bf16 v[34:37], v[154:157], v[170:173], v[34:37]
	v_mfma_f32_16x16x32_bf16 v[34:37], v[158:161], v[174:177], v[34:37]
	v_mfma_f32_16x16x32_bf16 v[38:41], v[150:153], v[174:177], v[38:41]
	v_mfma_f32_16x16x32_bf16 v[38:41], v[146:149], v[170:173], v[38:41]
	v_mfma_f32_16x16x32_bf16 v[20:23], v[146:149], v[178:181], v[20:23]
	v_mfma_f32_16x16x32_bf16 v[20:23], v[150:153], v[182:185], v[20:23]
	v_mfma_f32_16x16x32_bf16 v[16:19], v[158:161], v[182:185], v[16:19]
	v_mfma_f32_16x16x32_bf16 v[16:19], v[154:157], v[178:181], v[16:19]
	v_mfma_f32_16x16x32_bf16 v[0:3], v[154:157], v[186:189], v[0:3]
	v_mfma_f32_16x16x32_bf16 v[0:3], v[158:161], v[190:193], v[0:3]
	v_mfma_f32_16x16x32_bf16 v[4:7], v[150:153], v[190:193], v[4:7]
	v_mfma_f32_16x16x32_bf16 v[4:7], v[146:149], v[186:189], v[4:7]
	s_barrier
	s_add_i32 s51, s51, 2
	s_add_u32 s33, s33, 0x100
	s_addc_u32 s50, s50, 0
	s_cmpk_gt_u32 s51, 0x55
	s_mov_b64 s[4:5], s[6:7]
	s_cbranch_scc0 .LBB0_755
	s_setprio 0
	s_and_b64 vcc, exec, s[18:19]
	s_cbranch_vccz .LBB0_758
	s_barrier

.LBB0_887:
	s_add_u32 s50, s30, 0x100
	s_addc_u32 s51, s31, 0
	s_ashr_i32 s21, s20, 31
	s_lshl_b64 s[26:27], s[20:21], 20
	s_add_u32 s26, s10, s26
	s_addc_u32 s27, s11, s27
	s_and_b64 s[38:39], s[38:39], exec
	s_cselect_b32 s21, s27, s31
	s_cselect_b32 s52, s26, s30
	s_add_u32 s30, s16, 0x80080
	s_addc_u32 s31, s17, 0
	v_lshl_add_u64 v[130:131], s[30:31], 0, v[168:169]
	v_lshl_add_u64 v[132:133], s[30:31], 0, v[170:171]
	s_mov_b32 s53, -2
	s_mov_b64 s[30:31], 0
	s_and_b64 vcc, exec, s[18:19]
	s_cbranch_vccnz .Lprio_skip_888
	s_setprio 1
.Lprio_skip_888:
.LBB0_888:
	s_add_u32 s38, s16, s30
	s_addc_u32 s39, s17, s31
	s_add_u32 s38, s38, 0x100
	s_addc_u32 s39, s39, 0
	s_add_u32 s54, s50, s30
	s_addc_u32 s55, s51, s31
	s_add_i32 s56, 0, 0x10000
	s_cmpk_eq_i32 s30, 0xf00
	s_cselect_b32 s41, s29, s39
	s_cselect_b32 s40, s28, s38
	s_cselect_b32 s39, s21, s55
	s_cselect_b32 s38, s52, s54
	s_add_i32 s57, 0, 0x14000
	v_add_u32_e32 v146, s56, v178
	v_add_u32_e32 v172, s57, v178
	ds_read_b128 v[134:137], v146
	ds_read_b128 v[138:141], v146 offset:1024
	ds_read_b128 v[142:145], v146 offset:2048
	ds_read_b128 v[146:149], v146 offset:3072
	ds_read_b128 v[150:153], v172
	ds_read_b128 v[154:157], v172 offset:1024
	ds_read_b128 v[158:161], v172 offset:2048
	ds_read_b128 v[172:175], v172 offset:3072
	v_lshl_add_u64 v[212:213], v[130:131], 0, s[30:31]
	s_add_i32 m0, s24, 0xc000
	ds_read_b128 v[180:183], v179
	ds_read_b128 v[184:187], v179 offset:1024
	ds_read_b128 v[188:191], v179 offset:2048
	ds_read_b128 v[192:195], v179 offset:3072
	ds_read_b128 v[196:199], v179 offset:4096
	ds_read_b128 v[200:203], v179 offset:5120
	ds_read_b128 v[204:207], v179 offset:6144
	ds_read_b128 v[208:211], v179 offset:7168
	global_load_lds_dwordx4 v[212:213], off
	v_lshl_add_u64 v[212:213], v[132:133], 0, s[30:31]
	s_add_i32 m0, s24, 0xe000
	s_nop 0
	global_load_lds_dwordx4 v[212:213], off
	s_waitcnt vmcnt(8)
	s_waitcnt lgkmcnt(0)
	s_barrier
	v_mfma_f32_16x16x32_bf16 v[82:85], v[134:137], v[180:183], v[82:85]
	v_mfma_f32_16x16x32_bf16 v[82:85], v[138:141], v[184:187], v[82:85]
	v_mfma_f32_16x16x32_bf16 v[78:81], v[146:149], v[184:187], v[78:81]
	v_mfma_f32_16x16x32_bf16 v[78:81], v[142:145], v[180:183], v[78:81]
	v_mfma_f32_16x16x32_bf16 v[70:73], v[142:145], v[188:191], v[70:73]
	v_mfma_f32_16x16x32_bf16 v[70:73], v[146:149], v[192:195], v[70:73]
	v_mfma_f32_16x16x32_bf16 v[74:77], v[138:141], v[192:195], v[74:77]
	v_mfma_f32_16x16x32_bf16 v[74:77], v[134:137], v[188:191], v[74:77]
	v_mfma_f32_16x16x32_bf16 v[66:69], v[134:137], v[196:199], v[66:69]
	v_mfma_f32_16x16x32_bf16 v[66:69], v[138:141], v[200:203], v[66:69]
	v_mfma_f32_16x16x32_bf16 v[62:65], v[146:149], v[200:203], v[62:65]
	v_mfma_f32_16x16x32_bf16 v[62:65], v[142:145], v[196:199], v[62:65]
	v_mfma_f32_16x16x32_bf16 v[54:57], v[142:145], v[204:207], v[54:57]
	v_mfma_f32_16x16x32_bf16 v[54:57], v[146:149], v[208:211], v[54:57]
	v_mfma_f32_16x16x32_bf16 v[58:61], v[138:141], v[208:211], v[58:61]
	v_mfma_f32_16x16x32_bf16 v[58:61], v[134:137], v[204:207], v[58:61]
	v_mfma_f32_16x16x32_bf16 v[50:53], v[150:153], v[180:183], v[50:53]
	v_mfma_f32_16x16x32_bf16 v[50:53], v[154:157], v[184:187], v[50:53]
	v_mfma_f32_16x16x32_bf16 v[46:49], v[172:175], v[184:187], v[46:49]
	v_mfma_f32_16x16x32_bf16 v[46:49], v[158:161], v[180:183], v[46:49]
	v_mfma_f32_16x16x32_bf16 v[38:41], v[158:161], v[188:191], v[38:41]
	v_mfma_f32_16x16x32_bf16 v[38:41], v[172:175], v[192:195], v[38:41]
	v_mfma_f32_16x16x32_bf16 v[42:45], v[154:157], v[192:195], v[42:45]
	v_mfma_f32_16x16x32_bf16 v[42:45], v[150:153], v[188:191], v[42:45]
	v_mfma_f32_16x16x32_bf16 v[34:37], v[150:153], v[196:199], v[34:37]
	v_mfma_f32_16x16x32_bf16 v[34:37], v[154:157], v[200:203], v[34:37]
	v_mfma_f32_16x16x32_bf16 v[28:31], v[172:175], v[200:203], v[28:31]
	v_mfma_f32_16x16x32_bf16 v[28:31], v[158:161], v[196:199], v[28:31]
	v_mfma_f32_16x16x32_bf16 v[20:23], v[158:161], v[204:207], v[20:23]
	v_mfma_f32_16x16x32_bf16 v[20:23], v[172:175], v[208:211], v[20:23]
	v_mfma_f32_16x16x32_bf16 v[24:27], v[154:157], v[208:211], v[24:27]
	v_mfma_f32_16x16x32_bf16 v[24:27], v[150:153], v[204:207], v[24:27]
	s_barrier
	s_add_i32 s54, s56, s13
	v_lshl_add_u64 v[212:213], s[38:39], 0, v[32:33]
	s_mov_b32 m0, s54
	ds_read_b128 v[180:183], v179 offset:16384
	ds_read_b128 v[184:187], v179 offset:17408
	ds_read_b128 v[188:191], v179 offset:18432
	ds_read_b128 v[192:195], v179 offset:19456
	ds_read_b128 v[196:199], v179 offset:20480
	ds_read_b128 v[200:203], v179 offset:21504
	ds_read_b128 v[204:207], v179 offset:22528
	ds_read_b128 v[208:211], v179 offset:23552
	global_load_lds_dwordx4 v[212:213], off
	s_add_i32 m0, s54, 0x2000
	s_add_u32 s54, s38, 0x80000
	v_lshl_add_u64 v[214:215], s[38:39], 0, v[166:167]
	s_addc_u32 s55, s39, 0
	s_add_i32 s56, s57, s13
	global_load_lds_dwordx4 v[214:215], off
	s_mov_b32 m0, s56
	v_lshl_add_u64 v[220:221], s[40:41], 0, v[164:165]
	global_load_lds_dwordx4 v32, s[54:55]
	s_add_i32 m0, s56, 0x2000
	s_nop 0
	global_load_lds_dwordx4 v166, s[54:55]
	v_lshl_add_u64 v[216:217], s[40:41], 0, v[162:163]
	s_mov_b32 m0, s24
	s_nop 0
	global_load_lds_dwordx4 v[216:217], off
	s_mov_b32 m0, s25
	s_nop 0
	global_load_lds_dwordx4 v[220:221], off
	s_waitcnt vmcnt(8)
	s_waitcnt lgkmcnt(0)
	s_barrier
	v_mfma_f32_16x16x32_bf16 v[16:19], v[134:137], v[180:183], v[16:19]
	v_mfma_f32_16x16x32_bf16 v[16:19], v[138:141], v[184:187], v[16:19]
	v_mfma_f32_16x16x32_bf16 v[12:15], v[146:149], v[184:187], v[12:15]
	v_mfma_f32_16x16x32_bf16 v[12:15], v[142:145], v[180:183], v[12:15]
	v_mfma_f32_16x16x32_bf16 v[4:7], v[142:145], v[188:191], v[4:7]
	v_mfma_f32_16x16x32_bf16 v[4:7], v[146:149], v[192:195], v[4:7]
	v_mfma_f32_16x16x32_bf16 v[8:11], v[138:141], v[192:195], v[8:11]
	v_mfma_f32_16x16x32_bf16 v[8:11], v[134:137], v[188:191], v[8:11]
	v_mfma_f32_16x16x32_bf16 v[0:3], v[134:137], v[196:199], v[0:3]
	v_mfma_f32_16x16x32_bf16 v[0:3], v[138:141], v[200:203], v[0:3]
	v_mfma_f32_16x16x32_bf16 v[86:89], v[146:149], v[200:203], v[86:89]
	v_mfma_f32_16x16x32_bf16 v[86:89], v[142:145], v[196:199], v[86:89]
	v_mfma_f32_16x16x32_bf16 v[94:97], v[142:145], v[204:207], v[94:97]
	v_mfma_f32_16x16x32_bf16 v[94:97], v[146:149], v[208:211], v[94:97]
	v_mfma_f32_16x16x32_bf16 v[90:93], v[138:141], v[208:211], v[90:93]
	v_mfma_f32_16x16x32_bf16 v[90:93], v[134:137], v[204:207], v[90:93]
	v_mfma_f32_16x16x32_bf16 v[98:101], v[150:153], v[180:183], v[98:101]
	v_mfma_f32_16x16x32_bf16 v[98:101], v[154:157], v[184:187], v[98:101]
	v_mfma_f32_16x16x32_bf16 v[102:105], v[172:175], v[184:187], v[102:105]
	v_mfma_f32_16x16x32_bf16 v[102:105], v[158:161], v[180:183], v[102:105]
	v_mfma_f32_16x16x32_bf16 v[110:113], v[158:161], v[188:191], v[110:113]
	v_mfma_f32_16x16x32_bf16 v[110:113], v[172:175], v[192:195], v[110:113]
	v_mfma_f32_16x16x32_bf16 v[106:109], v[154:157], v[192:195], v[106:109]
	v_mfma_f32_16x16x32_bf16 v[106:109], v[150:153], v[188:191], v[106:109]
	v_mfma_f32_16x16x32_bf16 v[114:117], v[150:153], v[196:199], v[114:117]
	v_mfma_f32_16x16x32_bf16 v[114:117], v[154:157], v[200:203], v[114:117]
	v_mfma_f32_16x16x32_bf16 v[118:121], v[172:175], v[200:203], v[118:121]
	v_mfma_f32_16x16x32_bf16 v[118:121], v[158:161], v[196:199], v[118:121]
	v_mfma_f32_16x16x32_bf16 v[126:129], v[158:161], v[204:207], v[126:129]
	v_mfma_f32_16x16x32_bf16 v[126:129], v[172:175], v[208:211], v[126:129]
	v_mfma_f32_16x16x32_bf16 v[122:125], v[154:157], v[208:211], v[122:125]
	v_mfma_f32_16x16x32_bf16 v[122:125], v[150:153], v[204:207], v[122:125]
	s_barrier
	s_add_i32 s54, 0, 0x18000
	s_add_i32 s55, 0, 0x1c000
	v_add_u32_e32 v146, s54, v178
	v_add_u32_e32 v172, s55, v178
	ds_read_b128 v[134:137], v146
	ds_read_b128 v[138:141], v146 offset:1024
	ds_read_b128 v[142:145], v146 offset:2048
	ds_read_b128 v[146:149], v146 offset:3072
	ds_read_b128 v[150:153], v172
	ds_read_b128 v[154:157], v172 offset:1024
	ds_read_b128 v[158:161], v172 offset:2048
	ds_read_b128 v[172:175], v172 offset:3072
	s_add_u32 s40, s40, 0x80000
	s_addc_u32 s41, s41, 0
	s_mov_b32 m0, s33
	ds_read_b128 v[180:183], v179 offset:32768
	ds_read_b128 v[184:187], v179 offset:33792
	ds_read_b128 v[188:191], v179 offset:34816
	ds_read_b128 v[192:195], v179 offset:35840
	ds_read_b128 v[196:199], v179 offset:36864
	ds_read_b128 v[200:203], v179 offset:37888
	ds_read_b128 v[204:207], v179 offset:38912
	ds_read_b128 v[208:211], v179 offset:39936
	global_load_lds_dwordx4 v162, s[40:41]
	s_mov_b32 m0, s36
	s_nop 0
	global_load_lds_dwordx4 v164, s[40:41]
	s_waitcnt vmcnt(8)
	s_waitcnt lgkmcnt(0)
	s_barrier
	v_mfma_f32_16x16x32_bf16 v[82:85], v[134:137], v[180:183], v[82:85]
	v_mfma_f32_16x16x32_bf16 v[82:85], v[138:141], v[184:187], v[82:85]
	v_mfma_f32_16x16x32_bf16 v[78:81], v[146:149], v[184:187], v[78:81]
	v_mfma_f32_16x16x32_bf16 v[78:81], v[142:145], v[180:183], v[78:81]
	v_mfma_f32_16x16x32_bf16 v[70:73], v[142:145], v[188:191], v[70:73]
	v_mfma_f32_16x16x32_bf16 v[70:73], v[146:149], v[192:195], v[70:73]
	v_mfma_f32_16x16x32_bf16 v[74:77], v[138:141], v[192:195], v[74:77]
	v_mfma_f32_16x16x32_bf16 v[74:77], v[134:137], v[188:191], v[74:77]
	v_mfma_f32_16x16x32_bf16 v[66:69], v[134:137], v[196:199], v[66:69]
	v_mfma_f32_16x16x32_bf16 v[66:69], v[138:141], v[200:203], v[66:69]
	v_mfma_f32_16x16x32_bf16 v[62:65], v[146:149], v[200:203], v[62:65]
	v_mfma_f32_16x16x32_bf16 v[62:65], v[142:145], v[196:199], v[62:65]
	v_mfma_f32_16x16x32_bf16 v[54:57], v[142:145], v[204:207], v[54:57]
	v_mfma_f32_16x16x32_bf16 v[54:57], v[146:149], v[208:211], v[54:57]
	v_mfma_f32_16x16x32_bf16 v[58:61], v[138:141], v[208:211], v[58:61]
	v_mfma_f32_16x16x32_bf16 v[58:61], v[134:137], v[204:207], v[58:61]
	v_mfma_f32_16x16x32_bf16 v[50:53], v[150:153], v[180:183], v[50:53]
	v_mfma_f32_16x16x32_bf16 v[50:53], v[154:157], v[184:187], v[50:53]
	v_mfma_f32_16x16x32_bf16 v[46:49], v[172:175], v[184:187], v[46:49]
	v_mfma_f32_16x16x32_bf16 v[46:49], v[158:161], v[180:183], v[46:49]
	v_mfma_f32_16x16x32_bf16 v[38:41], v[158:161], v[188:191], v[38:41]
	v_mfma_f32_16x16x32_bf16 v[38:41], v[172:175], v[192:195], v[38:41]
	v_mfma_f32_16x16x32_bf16 v[42:45], v[154:157], v[192:195], v[42:45]
	v_mfma_f32_16x16x32_bf16 v[42:45], v[150:153], v[188:191], v[42:45]
	v_mfma_f32_16x16x32_bf16 v[34:37], v[150:153], v[196:199], v[34:37]
	v_mfma_f32_16x16x32_bf16 v[34:37], v[154:157], v[200:203], v[34:37]
	v_mfma_f32_16x16x32_bf16 v[28:31], v[172:175], v[200:203], v[28:31]
	v_mfma_f32_16x16x32_bf16 v[28:31], v[158:161], v[196:199], v[28:31]
	v_mfma_f32_16x16x32_bf16 v[20:23], v[158:161], v[204:207], v[20:23]
	v_mfma_f32_16x16x32_bf16 v[20:23], v[172:175], v[208:211], v[20:23]
	v_mfma_f32_16x16x32_bf16 v[24:27], v[154:157], v[208:211], v[24:27]
	v_mfma_f32_16x16x32_bf16 v[24:27], v[150:153], v[204:207], v[24:27]
	s_barrier
	s_add_i32 s40, s54, s13
	v_lshl_add_u64 v[212:213], v[212:213], 0, s[34:35]
	s_mov_b32 m0, s40
	ds_read_b128 v[180:183], v179 offset:49152
	ds_read_b128 v[184:187], v179 offset:50176
	ds_read_b128 v[188:191], v179 offset:51200
	ds_read_b128 v[192:195], v179 offset:52224
	ds_read_b128 v[196:199], v179 offset:53248
	ds_read_b128 v[200:203], v179 offset:54272
	ds_read_b128 v[204:207], v179 offset:55296
	ds_read_b128 v[208:211], v179 offset:56320
	global_load_lds_dwordx4 v[212:213], off
	s_add_i32 m0, s40, 0x2000
	s_add_u32 s38, s38, 0x80080
	v_lshl_add_u64 v[212:213], v[214:215], 0, s[34:35]
	s_addc_u32 s39, s39, 0
	s_add_i32 s40, s55, s13
	global_load_lds_dwordx4 v[212:213], off
	s_mov_b32 m0, s40
	s_nop 0
	global_load_lds_dwordx4 v32, s[38:39]
	s_add_i32 m0, s40, 0x2000
	s_nop 0
	global_load_lds_dwordx4 v166, s[38:39]
	v_lshl_add_u64 v[212:213], v[216:217], 0, s[34:35]
	s_mov_b32 m0, s43
	s_nop 0
	global_load_lds_dwordx4 v[212:213], off
	v_lshl_add_u64 v[212:213], v[220:221], 0, s[34:35]
	s_mov_b32 m0, s44
	s_nop 0
	global_load_lds_dwordx4 v[212:213], off
	s_waitcnt vmcnt(8)
	s_waitcnt lgkmcnt(0)
	s_barrier
	v_mfma_f32_16x16x32_bf16 v[16:19], v[134:137], v[180:183], v[16:19]
	v_mfma_f32_16x16x32_bf16 v[16:19], v[138:141], v[184:187], v[16:19]
	v_mfma_f32_16x16x32_bf16 v[12:15], v[146:149], v[184:187], v[12:15]
	v_mfma_f32_16x16x32_bf16 v[12:15], v[142:145], v[180:183], v[12:15]
	v_mfma_f32_16x16x32_bf16 v[4:7], v[142:145], v[188:191], v[4:7]
	v_mfma_f32_16x16x32_bf16 v[4:7], v[146:149], v[192:195], v[4:7]
	v_mfma_f32_16x16x32_bf16 v[8:11], v[138:141], v[192:195], v[8:11]
	v_mfma_f32_16x16x32_bf16 v[8:11], v[134:137], v[188:191], v[8:11]
	v_mfma_f32_16x16x32_bf16 v[0:3], v[134:137], v[196:199], v[0:3]
	v_mfma_f32_16x16x32_bf16 v[0:3], v[138:141], v[200:203], v[0:3]
	v_mfma_f32_16x16x32_bf16 v[86:89], v[146:149], v[200:203], v[86:89]
	v_mfma_f32_16x16x32_bf16 v[86:89], v[142:145], v[196:199], v[86:89]
	v_mfma_f32_16x16x32_bf16 v[94:97], v[142:145], v[204:207], v[94:97]
	v_mfma_f32_16x16x32_bf16 v[94:97], v[146:149], v[208:211], v[94:97]
	v_mfma_f32_16x16x32_bf16 v[90:93], v[138:141], v[208:211], v[90:93]
	v_mfma_f32_16x16x32_bf16 v[90:93], v[134:137], v[204:207], v[90:93]
	v_mfma_f32_16x16x32_bf16 v[98:101], v[150:153], v[180:183], v[98:101]
	v_mfma_f32_16x16x32_bf16 v[98:101], v[154:157], v[184:187], v[98:101]
	v_mfma_f32_16x16x32_bf16 v[102:105], v[172:175], v[184:187], v[102:105]
	v_mfma_f32_16x16x32_bf16 v[102:105], v[158:161], v[180:183], v[102:105]
	v_mfma_f32_16x16x32_bf16 v[110:113], v[158:161], v[188:191], v[110:113]
	v_mfma_f32_16x16x32_bf16 v[110:113], v[172:175], v[192:195], v[110:113]
	v_mfma_f32_16x16x32_bf16 v[106:109], v[154:157], v[192:195], v[106:109]
	v_mfma_f32_16x16x32_bf16 v[106:109], v[150:153], v[188:191], v[106:109]
	v_mfma_f32_16x16x32_bf16 v[114:117], v[150:153], v[196:199], v[114:117]
	v_mfma_f32_16x16x32_bf16 v[114:117], v[154:157], v[200:203], v[114:117]
	v_mfma_f32_16x16x32_bf16 v[118:121], v[172:175], v[200:203], v[118:121]
	v_mfma_f32_16x16x32_bf16 v[118:121], v[158:161], v[196:199], v[118:121]
	v_mfma_f32_16x16x32_bf16 v[126:129], v[158:161], v[204:207], v[126:129]
	v_mfma_f32_16x16x32_bf16 v[126:129], v[172:175], v[208:211], v[126:129]
	v_mfma_f32_16x16x32_bf16 v[122:125], v[154:157], v[208:211], v[122:125]
	v_mfma_f32_16x16x32_bf16 v[122:125], v[150:153], v[204:207], v[122:125]
	s_barrier
	s_add_i32 s53, s53, 2
	s_add_u32 s30, s30, 0x100
	s_addc_u32 s31, s31, 0
	s_cmp_gt_u32 s53, 29
	s_cbranch_scc0 .LBB0_888
	s_setprio 0
	s_and_b64 vcc, exec, s[18:19]
	s_cbranch_vccz .LBB0_891
	s_barrier
